# merge GEMM output stores write-through (sc1): lighter L2 write-back at the following grid barrier
# baseline (speedup 1.0000x reference)
; #define PG8_LDA(dst, b, h) do { _Pragma("unroll") for (int m = 0; m < 4; ++m) _Pragma("unroll") for (int k = 0; k < 2; ++k) dst[m][k] = *(const LAS bf16x8*)(lds + PG8_SA(b, h) + aoff + m * 2048 + k * 1024); } while (0)
; #define PG8_LDB(dst, b, h) do { _Pragma("unroll") for (int n = 0; n < 2; ++n) _Pragma("unroll") for (int k = 0; k < 2; ++k) dst[n][k] = *(const LAS bf16x8*)(lds + PG8_SB(b, h) + boff + n * 2048 + k * 1024); } while (0)
; #define PG8_MMA(ai, bj, At, Bt) do { __builtin_amdgcn_s_setprio(1); _Pragma("unroll") for (int m = 0; m < 4; ++m) _Pragma("unroll") for (int n = 0; n < 2; ++n) _Pragma("unroll") for (int k = 0; k < 2; ++k) \
;         acc[ai][bj][m][n] = __builtin_amdgcn_mfma_f32_16x16x32_bf16(Bt[n][k], At[m][k], acc[ai][bj][m][n], 0, 0, 0); __builtin_amdgcn_s_setprio(0); } while (0)
; #define PG8_WAIT_V(n) asm volatile("s_waitcnt vmcnt(" #n ")" ::: "memory")
; #define PG8_WAIT_L(n) asm volatile("s_waitcnt lgkmcnt(" #n ")" ::: "memory")
; #define PG8_BAR __builtin_amdgcn_s_barrier()
; #define PG8_SCHED __builtin_amdgcn_sched_barrier(0)
; #define PG8_STAGE2(bufoff, gbase, r2, Ksel) do { \
;         __builtin_amdgcn_global_load_lds((const unsigned*)((const char*)(gbase) + ((r2)[0] * (Ksel) + cb2[0])), (LAS unsigned*)(lds + (bufoff) + ldsw), 16, 0, 0); \
;         __builtin_amdgcn_global_load_lds((const unsigned*)((const char*)(gbase) + ((r2)[1] * (Ksel) + cb2[1])), (LAS unsigned*)(lds + (bufoff) + ldsw + 8192), 16, 0, 0); } while (0)
; #define PG8_BAR __builtin_amdgcn_s_barrier()
; template <class EpiMid, class EpiEnd>
; __device__ __forceinline__ void gemm_phase2(LAS unsigned char* lds, const Gemm g0, const Gemm g1, const StaticOrder& S, const EpiMid& Emid, const EpiEnd& Eend) {
;     ...
;                 PG8_LDB(B0, 0, 0); PG8_SCHED; PG8_LDA(At, 0, 0); PG8_STAGE2(PG8_SA(1, 1), a1 + hs, rA2, Kc);
;                 PG8_WAIT_L(8); PG8_BAR; PG8_WAIT_L(0); PG8_MMA(0, 0, At, B0); PG8_BAR; PG8_SCHED;
;                 PG8_LDB(B1, 0, 1); PG8_STAGE2(PG8_SB(0, 0), b2, rB2, K2);
;                 PG8_BAR; PG8_WAIT_L(0); PG8_MMA(0, 1, At, B1); PG8_BAR;
;                 PG8_LDA(At, 0, 1); PG8_STAGE2(PG8_SA(0, 0), a2, rA2, K2);
;                 PG8_BAR; PG8_WAIT_L(0); PG8_MMA(1, 0, At, B0); PG8_BAR; PG8_SCHED;
;                 PG8_STAGE2(PG8_SB(0, 1), b2 + h2, rB2, K2);
;                 PG8_WAIT_V(6); PG8_BAR; PG8_MMA(1, 1, At, B1); PG8_BAR;
.Lw6_skip:
	s_add_i32 s54, s54, 2
	s_add_u32 s26, s20, s24
	v_add_u32_e32 v0, s48, v159
	s_addc_u32 s27, s21, s25
	ds_read_b128 v[134:137], v0
	ds_read_b128 v[138:141], v0 offset:1024
	ds_read_b128 v[142:145], v0 offset:2048
	ds_read_b128 v[146:149], v0 offset:3072
	s_add_u32 s28, s26, 0x100
	s_addc_u32 s29, s27, 0
	s_and_b64 s[26:27], s[64:65], exec
	s_cselect_b32 s27, s56, s29
	s_cselect_b32 s26, s57, s28
	s_cselect_b32 s63, 0, 0
	s_cselect_b32 s66, s55, s53
	s_add_u32 s67, s60, s24
	s_addc_u32 s68, s61, s25
	s_and_b64 s[28:29], s[64:65], exec
	s_cselect_b32 s29, s58, s68
	s_cselect_b32 s28, s59, s67
	v_lshl_add_u64 v[150:151], v[2:3], 0, s[24:25]
	s_add_i32 m0, s36, 0xc000
	ds_read_b128 v[170:173], v165
	ds_read_b128 v[174:177], v165 offset:1024
	ds_read_b128 v[178:181], v165 offset:2048
	ds_read_b128 v[182:185], v165 offset:3072
	ds_read_b128 v[186:189], v165 offset:4096
	ds_read_b128 v[190:193], v165 offset:5120
	ds_read_b128 v[194:197], v165 offset:6144
	ds_read_b128 v[198:201], v165 offset:7168
	global_load_lds_dwordx4 v[150:151], off
	v_lshl_add_u64 v[150:151], v[132:133], 0, s[24:25]
	s_add_i32 m0, s36, 0xe000
	s_nop 0
	global_load_lds_dwordx4 v[150:151], off
	s_waitcnt lgkmcnt(8)
	s_barrier
	s_waitcnt lgkmcnt(0)
	s_setprio 1
	s_waitcnt lgkmcnt(0)
	v_mfma_f32_16x16x32_bf16 v[128:131], v[134:137], v[170:173], v[128:131]
	v_mfma_f32_16x16x32_bf16 v[124:127], v[142:145], v[170:173], v[124:127]
	v_mfma_f32_16x16x32_bf16 v[120:123], v[134:137], v[178:181], v[120:123]
	v_mfma_f32_16x16x32_bf16 v[116:119], v[142:145], v[178:181], v[116:119]
	v_mfma_f32_16x16x32_bf16 v[112:115], v[134:137], v[186:189], v[112:115]
	v_mfma_f32_16x16x32_bf16 v[108:111], v[142:145], v[186:189], v[108:111]
	v_mfma_f32_16x16x32_bf16 v[104:107], v[134:137], v[194:197], v[104:107]
	v_mfma_f32_16x16x32_bf16 v[100:103], v[142:145], v[194:197], v[100:103]
	v_mfma_f32_16x16x32_bf16 v[128:131], v[138:141], v[174:177], v[128:131]
	v_mfma_f32_16x16x32_bf16 v[124:127], v[146:149], v[174:177], v[124:127]
	v_mfma_f32_16x16x32_bf16 v[120:123], v[138:141], v[182:185], v[120:123]
	v_mfma_f32_16x16x32_bf16 v[116:119], v[146:149], v[182:185], v[116:119]
	v_mfma_f32_16x16x32_bf16 v[112:115], v[138:141], v[190:193], v[112:115]
	v_mfma_f32_16x16x32_bf16 v[108:111], v[146:149], v[190:193], v[108:111]
	v_mfma_f32_16x16x32_bf16 v[104:107], v[138:141], v[198:201], v[104:107]
	v_mfma_f32_16x16x32_bf16 v[100:103], v[146:149], v[198:201], v[100:103]
	s_setprio 0
	s_barrier
	s_xor_b64 s[64:65], s[22:23], s[64:65]
	s_and_b64 s[64:65], s[64:65], exec
	v_add_u32_e32 v0, s49, v159
	s_cselect_b32 s64, 10, 9
	s_add_i32 s65, s48, s33
	ds_read_b128 v[202:205], v0
	ds_read_b128 v[206:209], v0 offset:1024
	ds_read_b128 v[214:217], v0 offset:2048
	ds_read_b128 v[218:221], v0 offset:3072
	v_lshl_or_b32 v0, v156, s64, v154
	s_mov_b32 m0, s65
	v_lshl_or_b32 v150, v158, s64, v154
	global_load_lds_dwordx4 v0, s[28:29]
	s_add_i32 m0, s65, 0x2000
	v_mov_b32_e32 v151, v1
	global_load_lds_dwordx4 v150, s[28:29]
	s_barrier
	s_waitcnt lgkmcnt(0)
	v_lshl_add_u64 v[210:211], s[28:29], 0, v[0:1]
	v_lshl_add_u64 v[222:223], s[28:29], 0, v[150:151]
	s_setprio 1
	s_waitcnt lgkmcnt(0)
	v_mfma_f32_16x16x32_bf16 v[96:99], v[202:205], v[170:173], v[96:99]
	v_mfma_f32_16x16x32_bf16 v[92:95], v[214:217], v[170:173], v[92:95]
	v_mfma_f32_16x16x32_bf16 v[88:91], v[202:205], v[178:181], v[88:91]
	v_mfma_f32_16x16x32_bf16 v[84:87], v[214:217], v[178:181], v[84:87]
	v_mfma_f32_16x16x32_bf16 v[80:83], v[202:205], v[186:189], v[80:83]
	v_mfma_f32_16x16x32_bf16 v[76:79], v[214:217], v[186:189], v[76:79]
	v_mfma_f32_16x16x32_bf16 v[72:75], v[202:205], v[194:197], v[72:75]
	v_mfma_f32_16x16x32_bf16 v[68:71], v[214:217], v[194:197], v[68:71]
	v_mfma_f32_16x16x32_bf16 v[96:99], v[206:209], v[174:177], v[96:99]
	v_mfma_f32_16x16x32_bf16 v[92:95], v[218:221], v[174:177], v[92:95]
	v_mfma_f32_16x16x32_bf16 v[88:91], v[206:209], v[182:185], v[88:91]
	v_mfma_f32_16x16x32_bf16 v[84:87], v[218:221], v[182:185], v[84:87]
	v_mfma_f32_16x16x32_bf16 v[80:83], v[206:209], v[190:193], v[80:83]
	v_mfma_f32_16x16x32_bf16 v[76:79], v[218:221], v[190:193], v[76:79]
	v_mfma_f32_16x16x32_bf16 v[72:75], v[206:209], v[198:201], v[72:75]
	v_mfma_f32_16x16x32_bf16 v[68:71], v[218:221], v[198:201], v[68:71]
	s_setprio 0
	s_mov_b32 m0, s36
	v_lshl_or_b32 v224, v155, s64, v154
	s_barrier
	ds_read_b128 v[170:173], v165 offset:16384
	ds_read_b128 v[174:177], v165 offset:17408
	ds_read_b128 v[178:181], v165 offset:18432
	ds_read_b128 v[182:185], v165 offset:19456
	ds_read_b128 v[186:189], v165 offset:20480
	ds_read_b128 v[190:193], v165 offset:21504
	ds_read_b128 v[194:197], v165 offset:22528
	ds_read_b128 v[198:201], v165 offset:23552
	global_load_lds_dwordx4 v224, s[26:27]
	v_lshl_or_b32 v226, v157, s64, v154
	s_mov_b32 m0, s37
	v_mov_b32_e32 v225, v1
	global_load_lds_dwordx4 v226, s[26:27]
	s_barrier
	s_waitcnt lgkmcnt(0)
	v_mov_b32_e32 v227, v1
	v_lshl_add_u64 v[228:229], s[26:27], 0, v[224:225]
	v_lshl_add_u64 v[230:231], s[26:27], 0, v[226:227]
	s_setprio 1
	s_waitcnt lgkmcnt(0)
	v_mfma_f32_16x16x32_bf16 v[64:67], v[134:137], v[170:173], v[64:67]
	v_mfma_f32_16x16x32_bf16 v[60:63], v[142:145], v[170:173], v[60:63]
	v_mfma_f32_16x16x32_bf16 v[56:59], v[134:137], v[178:181], v[56:59]
	v_mfma_f32_16x16x32_bf16 v[52:55], v[142:145], v[178:181], v[52:55]
	v_mfma_f32_16x16x32_bf16 v[48:51], v[134:137], v[186:189], v[48:51]
	v_mfma_f32_16x16x32_bf16 v[44:47], v[142:145], v[186:189], v[44:47]
	v_mfma_f32_16x16x32_bf16 v[40:43], v[134:137], v[194:197], v[40:43]
	v_mfma_f32_16x16x32_bf16 v[36:39], v[142:145], v[194:197], v[36:39]
	v_mfma_f32_16x16x32_bf16 v[64:67], v[138:141], v[174:177], v[64:67]
	v_mfma_f32_16x16x32_bf16 v[60:63], v[146:149], v[174:177], v[60:63]
	v_mfma_f32_16x16x32_bf16 v[56:59], v[138:141], v[182:185], v[56:59]
	v_mfma_f32_16x16x32_bf16 v[52:55], v[146:149], v[182:185], v[52:55]
	v_mfma_f32_16x16x32_bf16 v[48:51], v[138:141], v[190:193], v[48:51]
	v_mfma_f32_16x16x32_bf16 v[44:47], v[146:149], v[190:193], v[44:47]
	v_mfma_f32_16x16x32_bf16 v[40:43], v[138:141], v[198:201], v[40:43]
	v_mfma_f32_16x16x32_bf16 v[36:39], v[146:149], v[198:201], v[36:39]
	s_setprio 0
	s_barrier
; #define PG8_LDA(dst, b, h) do { _Pragma("unroll") for (int m = 0; m < 4; ++m) _Pragma("unroll") for (int k = 0; k < 2; ++k) dst[m][k] = *(const LAS bf16x8*)(lds + PG8_SA(b, h) + aoff + m * 2048 + k * 1024); } while (0)
; #define PG8_LDB(dst, b, h) do { _Pragma("unroll") for (int n = 0; n < 2; ++n) _Pragma("unroll") for (int k = 0; k < 2; ++k) dst[n][k] = *(const LAS bf16x8*)(lds + PG8_SB(b, h) + boff + n * 2048 + k * 1024); } while (0)
; #define PG8_MMA(ai, bj, At, Bt) do { __builtin_amdgcn_s_setprio(1); _Pragma("unroll") for (int m = 0; m < 4; ++m) _Pragma("unroll") for (int n = 0; n < 2; ++n) _Pragma("unroll") for (int k = 0; k < 2; ++k) \
;         acc[ai][bj][m][n] = __builtin_amdgcn_mfma_f32_16x16x32_bf16(Bt[n][k], At[m][k], acc[ai][bj][m][n], 0, 0, 0); __builtin_amdgcn_s_setprio(0); } while (0)
; #define PG8_WAIT_V(n) asm volatile("s_waitcnt vmcnt(" #n ")" ::: "memory")
; #define PG8_WAIT_L(n) asm volatile("s_waitcnt lgkmcnt(" #n ")" ::: "memory")
; #define PG8_BAR __builtin_amdgcn_s_barrier()
; #define PG8_SCHED __builtin_amdgcn_sched_barrier(0)
; #define PG8_WAIT_V(n) asm volatile("s_waitcnt vmcnt(" #n ")" ::: "memory")
; #define PG8_WAIT_L(n) asm volatile("s_waitcnt lgkmcnt(" #n ")" ::: "memory")
; template <class EpiMid, class EpiEnd>
; __device__ __forceinline__ void gemm_phase2(LAS unsigned char* lds, const Gemm g0, const Gemm g1, const StaticOrder& S, const EpiMid& Emid, const EpiEnd& Eend) {
;     ...
;                 PG8_LDA(At, 0, 1); PG8_STAGE2(PG8_SA(0, 0), a2, rA2, K2);
;                 PG8_BAR; PG8_WAIT_L(0); PG8_MMA(1, 0, At, B0); PG8_BAR; PG8_SCHED;
;                 PG8_STAGE2(PG8_SB(0, 1), b2 + h2, rB2, K2);
;                 PG8_WAIT_V(6); PG8_BAR; PG8_MMA(1, 1, At, B1); PG8_BAR;
;                 PG8_LDB(B0, 1, 0); PG8_SCHED; PG8_LDA(At, 1, 0); PG8_STAGE2(PG8_SA(0, 1), a2 + h2, rA2, K2);
;                 PG8_WAIT_L(8); PG8_BAR; PG8_WAIT_L(0); PG8_MMA(0, 0, At, B0); PG8_BAR; PG8_SCHED;
;                 PG8_LDB(B1, 1, 1); PG8_STAGE2(PG8_SB(1, 0), b3, rB2, K2);
;                 PG8_BAR; PG8_WAIT_L(0); PG8_MMA(0, 1, At, B1); PG8_BAR;
;                 PG8_LDA(At, 1, 1); PG8_STAGE2(PG8_SA(1, 0), a3, rA2, K2);
;                 PG8_BAR; PG8_WAIT_L(0); PG8_MMA(1, 0, At, B0); PG8_BAR; PG8_SCHED;
;                 PG8_STAGE2(PG8_SB(1, 1), b3 + h2, rB2, K2);
;                 PG8_WAIT_V(6); PG8_BAR; PG8_MMA(1, 1, At, B1); PG8_BAR;
	s_add_u32 s28, s28, s66
	s_addc_u32 s29, s29, s63
	s_add_i32 s64, s49, s33
	s_mov_b32 m0, s64
	v_lshl_add_u64 v[232:233], s[28:29], 0, v[0:1]
	global_load_lds_dwordx4 v0, s[28:29]
	s_add_i32 m0, s64, 0x2000
	s_nop 0
	global_load_lds_dwordx4 v150, s[28:29]
	s_waitcnt vmcnt(6)
	v_lshl_add_u64 v[150:151], s[28:29], 0, v[150:151]
	s_barrier
	s_setprio 1
	v_mfma_f32_16x16x32_bf16 v[32:35], v[202:205], v[170:173], v[32:35]
	v_mfma_f32_16x16x32_bf16 v[28:31], v[214:217], v[170:173], v[28:31]
	v_mfma_f32_16x16x32_bf16 v[24:27], v[202:205], v[178:181], v[24:27]
	v_mfma_f32_16x16x32_bf16 v[20:23], v[214:217], v[178:181], v[20:23]
	v_mfma_f32_16x16x32_bf16 v[16:19], v[202:205], v[186:189], v[16:19]
	v_mfma_f32_16x16x32_bf16 v[12:15], v[214:217], v[186:189], v[12:15]
	v_mfma_f32_16x16x32_bf16 v[8:11], v[202:205], v[194:197], v[8:11]
	v_mfma_f32_16x16x32_bf16 v[4:7], v[214:217], v[194:197], v[4:7]
	v_mfma_f32_16x16x32_bf16 v[32:35], v[206:209], v[174:177], v[32:35]
	v_mfma_f32_16x16x32_bf16 v[28:31], v[218:221], v[174:177], v[28:31]
	v_mfma_f32_16x16x32_bf16 v[24:27], v[206:209], v[182:185], v[24:27]
	v_mfma_f32_16x16x32_bf16 v[20:23], v[218:221], v[182:185], v[20:23]
	v_mfma_f32_16x16x32_bf16 v[16:19], v[206:209], v[190:193], v[16:19]
	v_mfma_f32_16x16x32_bf16 v[12:15], v[218:221], v[190:193], v[12:15]
	v_mfma_f32_16x16x32_bf16 v[8:11], v[206:209], v[198:201], v[8:11]
	v_mfma_f32_16x16x32_bf16 v[4:7], v[218:221], v[198:201], v[4:7]
	s_setprio 0
	s_add_i32 s28, 0, 0x18000
	v_add_u32_e32 v0, s28, v159
	s_barrier
	ds_read_b128 v[134:137], v0
	ds_read_b128 v[138:141], v0 offset:1024
	ds_read_b128 v[142:145], v0 offset:2048
	ds_read_b128 v[146:149], v0 offset:3072
	s_add_u32 s26, s26, s66
	s_addc_u32 s27, s27, s63
	s_mov_b32 m0, s38
	ds_read_b128 v[170:173], v165 offset:32768
	ds_read_b128 v[174:177], v165 offset:33792
	ds_read_b128 v[178:181], v165 offset:34816
	ds_read_b128 v[182:185], v165 offset:35840
	ds_read_b128 v[186:189], v165 offset:36864
	ds_read_b128 v[190:193], v165 offset:37888
	ds_read_b128 v[194:197], v165 offset:38912
	ds_read_b128 v[198:201], v165 offset:39936
	global_load_lds_dwordx4 v224, s[26:27]
	s_mov_b32 m0, s39
	s_nop 0
	global_load_lds_dwordx4 v226, s[26:27]
	s_waitcnt lgkmcnt(8)
	s_barrier
	s_waitcnt lgkmcnt(0)
	s_setprio 1
	s_waitcnt lgkmcnt(0)
	v_mfma_f32_16x16x32_bf16 v[128:131], v[134:137], v[170:173], v[128:131]
	v_mfma_f32_16x16x32_bf16 v[124:127], v[142:145], v[170:173], v[124:127]
	v_mfma_f32_16x16x32_bf16 v[120:123], v[134:137], v[178:181], v[120:123]
	v_mfma_f32_16x16x32_bf16 v[116:119], v[142:145], v[178:181], v[116:119]
	v_mfma_f32_16x16x32_bf16 v[112:115], v[134:137], v[186:189], v[112:115]
	v_mfma_f32_16x16x32_bf16 v[108:111], v[142:145], v[186:189], v[108:111]
	v_mfma_f32_16x16x32_bf16 v[104:107], v[134:137], v[194:197], v[104:107]
	v_mfma_f32_16x16x32_bf16 v[100:103], v[142:145], v[194:197], v[100:103]
	v_mfma_f32_16x16x32_bf16 v[128:131], v[138:141], v[174:177], v[128:131]
	v_mfma_f32_16x16x32_bf16 v[124:127], v[146:149], v[174:177], v[124:127]
	v_mfma_f32_16x16x32_bf16 v[120:123], v[138:141], v[182:185], v[120:123]
	v_mfma_f32_16x16x32_bf16 v[116:119], v[146:149], v[182:185], v[116:119]
	v_mfma_f32_16x16x32_bf16 v[112:115], v[138:141], v[190:193], v[112:115]
	v_mfma_f32_16x16x32_bf16 v[108:111], v[146:149], v[190:193], v[108:111]
	v_mfma_f32_16x16x32_bf16 v[104:107], v[138:141], v[198:201], v[104:107]
	v_mfma_f32_16x16x32_bf16 v[100:103], v[146:149], v[198:201], v[100:103]
	s_setprio 0
	s_barrier
	s_add_i32 s26, 0, 0x1c000
	s_add_i32 s27, s28, s33
	v_add_u32_e32 v0, s26, v159
	v_lshl_add_u64 v[210:211], v[210:211], 0, s[8:9]
	s_mov_b32 m0, s27
	ds_read_b128 v[202:205], v0
	ds_read_b128 v[206:209], v0 offset:1024
	ds_read_b128 v[214:217], v0 offset:2048
	ds_read_b128 v[218:221], v0 offset:3072
	global_load_lds_dwordx4 v[210:211], off
	v_lshl_add_u64 v[210:211], v[222:223], 0, s[8:9]
	s_add_i32 m0, s27, 0x2000
	s_nop 0
	global_load_lds_dwordx4 v[210:211], off
	s_barrier
	s_waitcnt lgkmcnt(0)
	s_setprio 1
	s_waitcnt lgkmcnt(0)
	v_mfma_f32_16x16x32_bf16 v[96:99], v[202:205], v[170:173], v[96:99]
	v_mfma_f32_16x16x32_bf16 v[92:95], v[214:217], v[170:173], v[92:95]
	v_mfma_f32_16x16x32_bf16 v[88:91], v[202:205], v[178:181], v[88:91]
	v_mfma_f32_16x16x32_bf16 v[84:87], v[214:217], v[178:181], v[84:87]
	v_mfma_f32_16x16x32_bf16 v[80:83], v[202:205], v[186:189], v[80:83]
	v_mfma_f32_16x16x32_bf16 v[76:79], v[214:217], v[186:189], v[76:79]
	v_mfma_f32_16x16x32_bf16 v[72:75], v[202:205], v[194:197], v[72:75]
	v_mfma_f32_16x16x32_bf16 v[68:71], v[214:217], v[194:197], v[68:71]
	v_mfma_f32_16x16x32_bf16 v[96:99], v[206:209], v[174:177], v[96:99]
	v_mfma_f32_16x16x32_bf16 v[92:95], v[218:221], v[174:177], v[92:95]
	v_mfma_f32_16x16x32_bf16 v[88:91], v[206:209], v[182:185], v[88:91]
	v_mfma_f32_16x16x32_bf16 v[84:87], v[218:221], v[182:185], v[84:87]
	v_mfma_f32_16x16x32_bf16 v[80:83], v[206:209], v[190:193], v[80:83]
	v_mfma_f32_16x16x32_bf16 v[76:79], v[218:221], v[190:193], v[76:79]
	v_mfma_f32_16x16x32_bf16 v[72:75], v[206:209], v[198:201], v[72:75]
	v_mfma_f32_16x16x32_bf16 v[68:71], v[218:221], v[198:201], v[68:71]
	s_setprio 0
	s_mov_b32 m0, s43
	v_lshl_add_u64 v[210:211], v[228:229], 0, s[8:9]
	s_barrier
	ds_read_b128 v[170:173], v165 offset:49152
	ds_read_b128 v[174:177], v165 offset:50176
	ds_read_b128 v[178:181], v165 offset:51200
	ds_read_b128 v[182:185], v165 offset:52224
	ds_read_b128 v[186:189], v165 offset:53248
	ds_read_b128 v[190:193], v165 offset:54272
	ds_read_b128 v[194:197], v165 offset:55296
	ds_read_b128 v[198:201], v165 offset:56320
	global_load_lds_dwordx4 v[210:211], off
	v_lshl_add_u64 v[210:211], v[230:231], 0, s[8:9]
	s_mov_b32 m0, s44
	s_nop 0
	global_load_lds_dwordx4 v[210:211], off
	s_barrier
; __device__ __forceinline__ float sigmoidf_(float x) { return __builtin_amdgcn_rcpf(1.0f + __expf(-x)); }
; #define PG8_LDA(dst, b, h) do { _Pragma("unroll") for (int m = 0; m < 4; ++m) _Pragma("unroll") for (int k = 0; k < 2; ++k) dst[m][k] = *(const LAS bf16x8*)(lds + PG8_SA(b, h) + aoff + m * 2048 + k * 1024); } while (0)
; #define PG8_MMA(ai, bj, At, Bt) do { __builtin_amdgcn_s_setprio(1); _Pragma("unroll") for (int m = 0; m < 4; ++m) _Pragma("unroll") for (int n = 0; n < 2; ++n) _Pragma("unroll") for (int k = 0; k < 2; ++k) \
;         acc[ai][bj][m][n] = __builtin_amdgcn_mfma_f32_16x16x32_bf16(Bt[n][k], At[m][k], acc[ai][bj][m][n], 0, 0, 0); __builtin_amdgcn_s_setprio(0); } while (0)
; #define PG8_WAIT_V(n) asm volatile("s_waitcnt vmcnt(" #n ")" ::: "memory")
; #define PG8_WAIT_L(n) asm volatile("s_waitcnt lgkmcnt(" #n ")" ::: "memory")
; template <class EpiMid, class EpiEnd>
; __device__ __forceinline__ void gemm_phase2(LAS unsigned char* lds, const Gemm g0, const Gemm g1, const StaticOrder& S, const EpiMid& Emid, const EpiEnd& Eend) {
;     ...
;                 PG8_BAR; PG8_WAIT_L(0); PG8_MMA(0, 1, At, B1); PG8_BAR;
;                 PG8_LDA(At, 1, 1); PG8_STAGE2(PG8_SA(1, 0), a3, rA2, K2);
;                 PG8_BAR; PG8_WAIT_L(0); PG8_MMA(1, 0, At, B0); PG8_BAR; PG8_SCHED;
;                 PG8_STAGE2(PG8_SB(1, 1), b3 + h2, rB2, K2);
;                 PG8_WAIT_V(6); PG8_BAR; PG8_MMA(1, 1, At, B1); PG8_BAR;
;             }
;             if (seg == 0) Emid(acc, cur, wr, wc, fr, fq); else Eend(acc, cur, wr, wc, fr, fq);
;     __device__ __forceinline__ void operator()(f32x4 (&acc)[2][2][4][2], const pg8::Unit& u, int wr, int wc, int fr, int fq) const {
;     ...
;             u32x4 ga[4][2];
; #pragma unroll
;             for (int m = 0; m < 4; ++m)
; #pragma unroll
;                 for (int bj = 0; bj < 2; ++bj) ga[m][bj] = __builtin_nontemporal_load((const u32x4*)((const char*)Gt + (goff + (unsigned)(ai * 128 + m * 16) * 4096u + 256u * bj)));
; #pragma unroll
;             for (int m = 0; m < 4; ++m) {
;                 const unsigned rm = moff + (unsigned)(ai * 128 + m * 16) * 2048u;
; #pragma unroll
;                 for (int bj = 0; bj < 2; ++bj) {
;                     float fa[8], o[8]; unpack8(ga[m][bj], fa);
; #pragma unroll
;                     for (int e = 0; e < 8; ++e) o[e] = sigmoidf_(fa[e]) * acc[ai][bj][m][e >> 2][e & 3];
	s_waitcnt lgkmcnt(0)
	s_setprio 1
	s_waitcnt lgkmcnt(0)
	v_mfma_f32_16x16x32_bf16 v[64:67], v[134:137], v[170:173], v[64:67]
	v_mfma_f32_16x16x32_bf16 v[60:63], v[142:145], v[170:173], v[60:63]
	v_mfma_f32_16x16x32_bf16 v[56:59], v[134:137], v[178:181], v[56:59]
	v_mfma_f32_16x16x32_bf16 v[52:55], v[142:145], v[178:181], v[52:55]
	v_mfma_f32_16x16x32_bf16 v[48:51], v[134:137], v[186:189], v[48:51]
	v_mfma_f32_16x16x32_bf16 v[44:47], v[142:145], v[186:189], v[44:47]
	v_mfma_f32_16x16x32_bf16 v[40:43], v[134:137], v[194:197], v[40:43]
	v_mfma_f32_16x16x32_bf16 v[36:39], v[142:145], v[194:197], v[36:39]
	v_mfma_f32_16x16x32_bf16 v[64:67], v[138:141], v[174:177], v[64:67]
	v_mfma_f32_16x16x32_bf16 v[60:63], v[146:149], v[174:177], v[60:63]
	v_mfma_f32_16x16x32_bf16 v[56:59], v[138:141], v[182:185], v[56:59]
	v_mfma_f32_16x16x32_bf16 v[52:55], v[146:149], v[182:185], v[52:55]
	v_mfma_f32_16x16x32_bf16 v[48:51], v[138:141], v[190:193], v[48:51]
	v_mfma_f32_16x16x32_bf16 v[44:47], v[146:149], v[190:193], v[44:47]
	v_mfma_f32_16x16x32_bf16 v[40:43], v[138:141], v[198:201], v[40:43]
	v_mfma_f32_16x16x32_bf16 v[36:39], v[146:149], v[198:201], v[36:39]
	s_setprio 0
	s_barrier
	s_add_i32 s26, s26, s33
	v_lshl_add_u64 v[134:135], v[232:233], 0, s[8:9]
	s_mov_b32 m0, s26
	s_nop 0
	global_load_lds_dwordx4 v[134:135], off
	v_lshl_add_u64 v[134:135], v[150:151], 0, s[8:9]
	s_add_i32 m0, s26, 0x2000
	s_nop 0
	global_load_lds_dwordx4 v[134:135], off
	s_waitcnt vmcnt(6)
	s_barrier
	s_setprio 1
	v_mfma_f32_16x16x32_bf16 v[32:35], v[202:205], v[170:173], v[32:35]
	v_mfma_f32_16x16x32_bf16 v[28:31], v[214:217], v[170:173], v[28:31]
	v_mfma_f32_16x16x32_bf16 v[24:27], v[202:205], v[178:181], v[24:27]
	v_mfma_f32_16x16x32_bf16 v[20:23], v[214:217], v[178:181], v[20:23]
	v_mfma_f32_16x16x32_bf16 v[16:19], v[202:205], v[186:189], v[16:19]
	v_mfma_f32_16x16x32_bf16 v[12:15], v[214:217], v[186:189], v[12:15]
	v_mfma_f32_16x16x32_bf16 v[8:11], v[202:205], v[194:197], v[8:11]
	v_mfma_f32_16x16x32_bf16 v[4:7], v[214:217], v[194:197], v[4:7]
	v_mfma_f32_16x16x32_bf16 v[32:35], v[206:209], v[174:177], v[32:35]
	v_mfma_f32_16x16x32_bf16 v[28:31], v[218:221], v[174:177], v[28:31]
	v_mfma_f32_16x16x32_bf16 v[24:27], v[206:209], v[182:185], v[24:27]
	v_mfma_f32_16x16x32_bf16 v[20:23], v[218:221], v[182:185], v[20:23]
	v_mfma_f32_16x16x32_bf16 v[16:19], v[206:209], v[190:193], v[16:19]
	v_mfma_f32_16x16x32_bf16 v[12:15], v[218:221], v[190:193], v[12:15]
	v_mfma_f32_16x16x32_bf16 v[8:11], v[206:209], v[198:201], v[8:11]
	v_mfma_f32_16x16x32_bf16 v[4:7], v[218:221], v[198:201], v[4:7]
	s_setprio 0
	s_add_u32 s24, s24, 0x100
	s_addc_u32 s25, s25, 0
	s_cmp_ge_u32 s54, s52
	s_barrier
	s_cbranch_scc0 .LBB0_772
	s_mov_b64 s[20:21], -1
	s_and_b64 vcc, exec, s[18:19]
	s_cbranch_vccz .LBB0_775
	v_mov_b32_e32 v2, v166
	v_mov_b32_e32 v0, v167
	global_load_dwordx4 v[170:173], v2, s[94:95] nt
	v_add_u32_e32 v3, 0x100, v2
	global_load_dwordx4 v[174:177], v3, s[94:95] nt
	v_add_u32_e32 v3, 0x10000, v2
	v_add_u32_e32 v132, 0x10100, v2
	v_add_u32_e32 v133, 0x20000, v2
	v_add_u32_e32 v134, 0x20100, v2
	v_add_u32_e32 v135, 0x30000, v2
	v_add_u32_e32 v169, 0x30100, v2
	global_load_dwordx4 v[178:181], v3, s[94:95] nt
	global_load_dwordx4 v[148:151], v132, s[94:95] nt
	global_load_dwordx4 v[144:147], v133, s[94:95] nt
	global_load_dwordx4 v[140:143], v134, s[94:95] nt
	global_load_dwordx4 v[136:139], v135, s[94:95] nt
	s_nop 0
	global_load_dwordx4 v[132:135], v169, s[94:95] nt
	s_mov_b64 s[20:21], 0
	s_waitcnt vmcnt(0)
	v_lshlrev_b32_e32 v3, 16, v170
	v_and_b32_e32 v169, 0xffff0000, v170
	v_lshlrev_b32_e32 v170, 16, v171
	v_and_b32_e32 v171, 0xffff0000, v171
	v_lshlrev_b32_e32 v182, 16, v172
	v_and_b32_e32 v172, 0xffff0000, v172
	v_lshlrev_b32_e32 v183, 16, v173
	v_and_b32_e32 v173, 0xffff0000, v173
	v_mul_f32_e32 v3, 0xbfb8aa3b, v3
	v_mul_f32_e32 v169, 0xbfb8aa3b, v169
	v_mul_f32_e32 v170, 0xbfb8aa3b, v170
	v_mul_f32_e32 v171, 0xbfb8aa3b, v171
	v_mul_f32_e32 v182, 0xbfb8aa3b, v182
	v_mul_f32_e32 v172, 0xbfb8aa3b, v172
	v_mul_f32_e32 v183, 0xbfb8aa3b, v183
	v_mul_f32_e32 v173, 0xbfb8aa3b, v173
	v_lshlrev_b32_e32 v187, 16, v177
	v_and_b32_e32 v188, 0xffff0000, v177
	v_exp_f32_e32 v3, v3
	v_exp_f32_e32 v169, v169
	v_exp_f32_e32 v170, v170
	v_exp_f32_e32 v171, v171
	v_exp_f32_e32 v177, v182
	v_exp_f32_e32 v172, v172
	v_exp_f32_e32 v182, v183
	v_exp_f32_e32 v173, v173
	v_lshlrev_b32_e32 v184, 16, v174
	v_and_b32_e32 v174, 0xffff0000, v174
	v_lshlrev_b32_e32 v185, 16, v175
	v_and_b32_e32 v175, 0xffff0000, v175
	v_lshlrev_b32_e32 v186, 16, v176
	v_and_b32_e32 v176, 0xffff0000, v176
	v_mul_f32_e32 v174, 0xbfb8aa3b, v174
	v_mul_f32_e32 v175, 0xbfb8aa3b, v175
	v_mul_f32_e32 v176, 0xbfb8aa3b, v176
	v_mul_f32_e32 v183, 0xbfb8aa3b, v184
	v_mul_f32_e32 v184, 0xbfb8aa3b, v185
	v_mul_f32_e32 v185, 0xbfb8aa3b, v186
	v_exp_f32_e32 v186, v174
	v_exp_f32_e32 v189, v175
	v_exp_f32_e32 v190, v176
	v_add_f32_e32 v3, 1.0, v3
	v_add_f32_e32 v169, 1.0, v169
	v_add_f32_e32 v174, 1.0, v170
	v_add_f32_e32 v175, 1.0, v171
	v_add_f32_e32 v176, 1.0, v177
	v_add_f32_e32 v177, 1.0, v172
	v_add_f32_e32 v182, 1.0, v182
	v_add_f32_e32 v191, 1.0, v173
	v_rcp_f32_e32 v170, v3
	v_rcp_f32_e32 v171, v169
	v_rcp_f32_e32 v172, v174
	v_rcp_f32_e32 v173, v175
	v_rcp_f32_e32 v174, v176
	v_rcp_f32_e32 v175, v177
	v_rcp_f32_e32 v176, v182
	v_rcp_f32_e32 v177, v191
	v_exp_f32_e32 v183, v183
	v_add_f32_e32 v169, 1.0, v186
	v_pk_mul_f32 v[170:171], v[128:129], v[170:171]
	v_pk_mul_f32 v[172:173], v[130:131], v[172:173]
	v_pk_mul_f32 v[174:175], v[124:125], v[174:175]
	v_pk_mul_f32 v[176:177], v[126:127], v[176:177]
	v_add_f32_e32 v3, 1.0, v183
; __device__ __forceinline__ float sigmoidf_(float x) { return __builtin_amdgcn_rcpf(1.0f + __expf(-x)); }
;     __device__ __forceinline__ void operator()(f32x4 (&acc)[2][2][4][2], const pg8::Unit& u, int wr, int wc, int fr, int fq) const {
;     ...
;             for (int m = 0; m < 4; ++m) {
;                 const unsigned rm = moff + (unsigned)(ai * 128 + m * 16) * 2048u;
; #pragma unroll
;                 for (int bj = 0; bj < 2; ++bj) {
;                     float fa[8], o[8]; unpack8(ga[m][bj], fa);
; #pragma unroll
;                     for (int e = 0; e < 8; ++e) o[e] = sigmoidf_(fa[e]) * acc[ai][bj][m][e >> 2][e & 3];
;                     *(u32x4*)((char*)MG + (rm + 256u * bj)) = pack8(o);
;                 }
	v_rcp_f32_e32 v183, v169
	v_cvt_pk_bf16_f32 v170, v170, v171
	v_cvt_pk_bf16_f32 v171, v172, v173
	v_cvt_pk_bf16_f32 v172, v174, v175
	v_cvt_pk_bf16_f32 v173, v176, v177
	v_mul_f32_e32 v169, 0xbfb8aa3b, v187
	global_store_dwordx4 v0, v[170:173], s[4:5] sc1
	v_exp_f32_e32 v169, v169
	v_exp_f32_e32 v184, v184
	v_mul_f32_e32 v171, 0xbfb8aa3b, v188
	v_exp_f32_e32 v185, v185
	v_exp_f32_e32 v173, v171
	v_rcp_f32_e32 v182, v3
	v_add_f32_e32 v3, 1.0, v190
	v_rcp_f32_e32 v171, v3
	v_add_f32_e32 v3, 1.0, v169
	v_add_f32_e32 v184, 1.0, v184
	v_add_f32_e32 v186, 1.0, v189
	v_add_f32_e32 v189, 1.0, v185
	v_rcp_f32_e32 v172, v3
	v_add_f32_e32 v3, 1.0, v173
	v_rcp_f32_e32 v184, v184
	v_rcp_f32_e32 v185, v186
	v_rcp_f32_e32 v170, v189
	v_rcp_f32_e32 v173, v3
	v_pk_mul_f32 v[174:175], v[96:97], v[182:183]
	v_pk_mul_f32 v[176:177], v[98:99], v[184:185]
	v_pk_mul_f32 v[182:183], v[92:93], v[170:171]
	v_pk_mul_f32 v[184:185], v[94:95], v[172:173]
	v_cvt_pk_bf16_f32 v170, v174, v175
	v_cvt_pk_bf16_f32 v171, v176, v177
	v_cvt_pk_bf16_f32 v172, v182, v183
	v_cvt_pk_bf16_f32 v173, v184, v185
	v_add_u32_e32 v3, 0x100, v0
	v_lshlrev_b32_e32 v169, 16, v178
	global_store_dwordx4 v3, v[170:173], s[4:5] sc1
	v_mul_f32_e32 v169, 0xbfb8aa3b, v169
	v_exp_f32_e32 v169, v169
	v_and_b32_e32 v170, 0xffff0000, v178
	v_mul_f32_e32 v170, 0xbfb8aa3b, v170
	v_exp_f32_e32 v176, v170
	v_lshlrev_b32_e32 v171, 16, v179
	v_add_f32_e32 v169, 1.0, v169
	v_mul_f32_e32 v171, 0xbfb8aa3b, v171
	v_rcp_f32_e32 v170, v169
	v_add_f32_e32 v169, 1.0, v176
	v_exp_f32_e32 v176, v171
	v_and_b32_e32 v172, 0xffff0000, v179
	v_lshlrev_b32_e32 v173, 16, v180
	v_mul_f32_e32 v171, 0xbfb8aa3b, v172
	v_exp_f32_e32 v178, v171
	v_mul_f32_e32 v173, 0xbfb8aa3b, v173
	v_rcp_f32_e32 v171, v169
	v_add_f32_e32 v169, 1.0, v176
	v_exp_f32_e32 v176, v173
	v_and_b32_e32 v174, 0xffff0000, v180
	v_lshlrev_b32_e32 v175, 16, v181
	v_mul_f32_e32 v173, 0xbfb8aa3b, v174
	v_and_b32_e32 v177, 0xffff0000, v181
	v_rcp_f32_e32 v172, v169
	v_add_f32_e32 v169, 1.0, v178
	v_exp_f32_e32 v178, v173
	v_mul_f32_e32 v175, 0xbfb8aa3b, v175
	v_rcp_f32_e32 v173, v169
	v_add_f32_e32 v169, 1.0, v176
	v_exp_f32_e32 v176, v175
	v_mul_f32_e32 v175, 0xbfb8aa3b, v177
	v_exp_f32_e32 v177, v175
	v_rcp_f32_e32 v174, v169
	v_add_f32_e32 v169, 1.0, v178
	v_rcp_f32_e32 v175, v169
	v_add_f32_e32 v169, 1.0, v176
	v_rcp_f32_e32 v176, v169
	v_add_f32_e32 v169, 1.0, v177
	v_rcp_f32_e32 v177, v169
	v_pk_mul_f32 v[170:171], v[120:121], v[170:171]
	v_pk_mul_f32 v[172:173], v[122:123], v[172:173]
	v_pk_mul_f32 v[174:175], v[116:117], v[174:175]
	v_pk_mul_f32 v[176:177], v[118:119], v[176:177]
	v_add_u32_e32 v3, 0x8000, v0
	v_cvt_pk_bf16_f32 v170, v170, v171
	v_cvt_pk_bf16_f32 v171, v172, v173
	v_cvt_pk_bf16_f32 v172, v174, v175
	v_cvt_pk_bf16_f32 v173, v176, v177
	global_store_dwordx4 v3, v[170:173], s[4:5] sc1
	v_lshlrev_b32_e32 v3, 16, v148
	v_and_b32_e32 v148, 0xffff0000, v148
	v_mul_f32_e32 v3, 0xbfb8aa3b, v3
	v_exp_f32_e32 v3, v3
	v_mul_f32_e32 v148, 0xbfb8aa3b, v148
	v_lshlrev_b32_e32 v170, 16, v150
	v_and_b32_e32 v171, 0xffff0000, v150
	v_exp_f32_e32 v150, v148
	v_lshlrev_b32_e32 v169, 16, v149
	v_add_f32_e32 v3, 1.0, v3
	v_and_b32_e32 v149, 0xffff0000, v149
	v_rcp_f32_e32 v148, v3
	v_add_f32_e32 v3, 1.0, v150
	v_mul_f32_e32 v150, 0xbfb8aa3b, v169
	v_exp_f32_e32 v150, v150
	v_mul_f32_e32 v149, 0xbfb8aa3b, v149
	v_lshlrev_b32_e32 v172, 16, v151
	v_and_b32_e32 v173, 0xffff0000, v151
	v_exp_f32_e32 v151, v149
	v_rcp_f32_e32 v149, v3
	v_add_f32_e32 v3, 1.0, v150
	v_rcp_f32_e32 v150, v3
	v_add_f32_e32 v3, 1.0, v151
	v_mul_f32_e32 v151, 0xbfb8aa3b, v170
	v_exp_f32_e32 v169, v151
	v_mul_f32_e32 v151, 0xbfb8aa3b, v171
	v_exp_f32_e32 v171, v151
	v_rcp_f32_e32 v151, v3
	v_add_f32_e32 v3, 1.0, v169
	v_mul_f32_e32 v169, 0xbfb8aa3b, v172
	v_rcp_f32_e32 v170, v3
	v_add_f32_e32 v3, 1.0, v171
	v_exp_f32_e32 v169, v169
	v_mul_f32_e32 v171, 0xbfb8aa3b, v173
	v_exp_f32_e32 v173, v171
	v_rcp_f32_e32 v171, v3
	v_add_f32_e32 v3, 1.0, v169
	v_rcp_f32_e32 v172, v3
	v_add_f32_e32 v3, 1.0, v173
	v_rcp_f32_e32 v173, v3
	v_pk_mul_f32 v[148:149], v[88:89], v[148:149]
	v_pk_mul_f32 v[150:151], v[90:91], v[150:151]
	v_pk_mul_f32 v[170:171], v[84:85], v[170:171]
	v_pk_mul_f32 v[172:173], v[86:87], v[172:173]
	v_cvt_pk_bf16_f32 v148, v148, v149
	v_cvt_pk_bf16_f32 v149, v150, v151
	v_cvt_pk_bf16_f32 v150, v170, v171
	v_cvt_pk_bf16_f32 v151, v172, v173
	v_add_u32_e32 v3, 0x8100, v0
	global_store_dwordx4 v3, v[148:151], s[4:5] sc1
	v_lshlrev_b32_e32 v169, 16, v147
	v_and_b32_e32 v170, 0xffff0000, v147
	v_lshlrev_b32_e32 v148, 16, v144
	v_and_b32_e32 v144, 0xffff0000, v144
	v_lshlrev_b32_e32 v150, 16, v146
	v_and_b32_e32 v151, 0xffff0000, v146
	v_mul_f32_e32 v146, 0xbfb8aa3b, v148
	v_mul_f32_e32 v144, 0xbfb8aa3b, v144
	v_exp_f32_e32 v146, v146
	v_exp_f32_e32 v148, v144
	v_lshlrev_b32_e32 v149, 16, v145
	v_and_b32_e32 v145, 0xffff0000, v145
	v_mul_f32_e32 v147, 0xbfb8aa3b, v149
	v_mul_f32_e32 v145, 0xbfb8aa3b, v145
	v_add_f32_e32 v144, 1.0, v146
	v_add_f32_e32 v146, 1.0, v148
	v_exp_f32_e32 v147, v147
	v_exp_f32_e32 v148, v145
	v_rcp_f32_e32 v145, v146
	v_mul_f32_e32 v149, 0xbfb8aa3b, v151
	v_add_f32_e32 v146, 1.0, v147
	v_add_f32_e32 v147, 1.0, v148
	v_mul_f32_e32 v148, 0xbfb8aa3b, v150
	v_mul_f32_e32 v150, 0xbfb8aa3b, v169
	v_mul_f32_e32 v151, 0xbfb8aa3b, v170
	v_exp_f32_e32 v148, v148
	v_exp_f32_e32 v149, v149
	v_exp_f32_e32 v150, v150
	v_exp_f32_e32 v151, v151
	v_add_f32_e32 v148, 1.0, v148
	v_add_f32_e32 v149, 1.0, v149
	v_add_f32_e32 v150, 1.0, v150
	v_add_f32_e32 v151, 1.0, v151
	v_rcp_f32_e32 v144, v144
	v_rcp_f32_e32 v146, v146
	v_rcp_f32_e32 v147, v147
	v_rcp_f32_e32 v148, v148
; __device__ __forceinline__ float sigmoidf_(float x) { return __builtin_amdgcn_rcpf(1.0f + __expf(-x)); }
;     __device__ __forceinline__ void operator()(f32x4 (&acc)[2][2][4][2], const pg8::Unit& u, int wr, int wc, int fr, int fq) const {
;     ...
;             for (int m = 0; m < 4; ++m) {
;                 const unsigned rm = moff + (unsigned)(ai * 128 + m * 16) * 2048u;
; #pragma unroll
;                 for (int bj = 0; bj < 2; ++bj) {
;                     float fa[8], o[8]; unpack8(ga[m][bj], fa);
; #pragma unroll
;                     for (int e = 0; e < 8; ++e) o[e] = sigmoidf_(fa[e]) * acc[ai][bj][m][e >> 2][e & 3];
;                     *(u32x4*)((char*)MG + (rm + 256u * bj)) = pack8(o);
;                 }
	v_rcp_f32_e32 v149, v149
	v_rcp_f32_e32 v150, v150
	v_rcp_f32_e32 v151, v151
	v_pk_mul_f32 v[144:145], v[112:113], v[144:145]
	v_pk_mul_f32 v[146:147], v[114:115], v[146:147]
	v_pk_mul_f32 v[148:149], v[108:109], v[148:149]
	v_pk_mul_f32 v[150:151], v[110:111], v[150:151]
	v_add_u32_e32 v3, 0x10000, v0
	v_cvt_pk_bf16_f32 v144, v144, v145
	v_cvt_pk_bf16_f32 v145, v146, v147
	v_cvt_pk_bf16_f32 v146, v148, v149
	v_cvt_pk_bf16_f32 v147, v150, v151
	global_store_dwordx4 v3, v[144:147], s[4:5] sc1
	v_lshlrev_b32_e32 v3, 16, v140
	v_and_b32_e32 v140, 0xffff0000, v140
	v_mul_f32_e32 v3, 0xbfb8aa3b, v3
	v_exp_f32_e32 v3, v3
	v_mul_f32_e32 v140, 0xbfb8aa3b, v140
	v_lshlrev_b32_e32 v145, 16, v142
	v_and_b32_e32 v146, 0xffff0000, v142
	v_exp_f32_e32 v142, v140
	v_lshlrev_b32_e32 v144, 16, v141
	v_add_f32_e32 v3, 1.0, v3
	v_and_b32_e32 v141, 0xffff0000, v141
	v_rcp_f32_e32 v140, v3
	v_add_f32_e32 v3, 1.0, v142
	v_mul_f32_e32 v142, 0xbfb8aa3b, v144
	v_exp_f32_e32 v142, v142
	v_mul_f32_e32 v141, 0xbfb8aa3b, v141
	v_lshlrev_b32_e32 v147, 16, v143
	v_and_b32_e32 v148, 0xffff0000, v143
	v_exp_f32_e32 v143, v141
	v_rcp_f32_e32 v141, v3
	v_add_f32_e32 v3, 1.0, v142
	v_rcp_f32_e32 v142, v3
	v_add_f32_e32 v3, 1.0, v143
	v_mul_f32_e32 v143, 0xbfb8aa3b, v145
	v_exp_f32_e32 v144, v143
	v_mul_f32_e32 v143, 0xbfb8aa3b, v146
	v_exp_f32_e32 v145, v143
	v_rcp_f32_e32 v143, v3
	v_add_f32_e32 v3, 1.0, v144
	v_rcp_f32_e32 v144, v3
	v_add_f32_e32 v3, 1.0, v145
	v_mul_f32_e32 v145, 0xbfb8aa3b, v147
	v_exp_f32_e32 v146, v145
	v_mul_f32_e32 v145, 0xbfb8aa3b, v148
	v_exp_f32_e32 v147, v145
	v_rcp_f32_e32 v145, v3
	v_add_f32_e32 v3, 1.0, v146
	v_rcp_f32_e32 v146, v3
	v_add_f32_e32 v3, 1.0, v147
	v_rcp_f32_e32 v147, v3
	v_pk_mul_f32 v[140:141], v[80:81], v[140:141]
	v_pk_mul_f32 v[142:143], v[82:83], v[142:143]
	v_pk_mul_f32 v[144:145], v[76:77], v[144:145]
	v_pk_mul_f32 v[146:147], v[78:79], v[146:147]
	v_cvt_pk_bf16_f32 v140, v140, v141
	v_cvt_pk_bf16_f32 v141, v142, v143
	v_cvt_pk_bf16_f32 v142, v144, v145
	v_cvt_pk_bf16_f32 v143, v146, v147
	v_add_u32_e32 v3, 0x10100, v0
	global_store_dwordx4 v3, v[140:143], s[4:5] sc1
	v_lshlrev_b32_e32 v144, 16, v139
	v_and_b32_e32 v145, 0xffff0000, v139
	v_lshlrev_b32_e32 v140, 16, v136
	v_and_b32_e32 v136, 0xffff0000, v136
	v_lshlrev_b32_e32 v142, 16, v138
	v_and_b32_e32 v143, 0xffff0000, v138
	v_mul_f32_e32 v138, 0xbfb8aa3b, v140
	v_mul_f32_e32 v136, 0xbfb8aa3b, v136
	v_exp_f32_e32 v138, v138
	v_exp_f32_e32 v140, v136
	v_lshlrev_b32_e32 v141, 16, v137
	v_and_b32_e32 v137, 0xffff0000, v137
	v_mul_f32_e32 v139, 0xbfb8aa3b, v141
	v_mul_f32_e32 v137, 0xbfb8aa3b, v137
	v_add_f32_e32 v136, 1.0, v138
	v_add_f32_e32 v138, 1.0, v140
	v_exp_f32_e32 v139, v139
	v_exp_f32_e32 v140, v137
	v_rcp_f32_e32 v137, v138
	v_mul_f32_e32 v141, 0xbfb8aa3b, v143
	v_add_f32_e32 v138, 1.0, v139
	v_add_f32_e32 v139, 1.0, v140
	v_mul_f32_e32 v140, 0xbfb8aa3b, v142
	v_mul_f32_e32 v142, 0xbfb8aa3b, v144
	v_mul_f32_e32 v143, 0xbfb8aa3b, v145
	v_exp_f32_e32 v140, v140
	v_exp_f32_e32 v141, v141
	v_exp_f32_e32 v142, v142
	v_exp_f32_e32 v143, v143
	v_add_f32_e32 v140, 1.0, v140
	v_add_f32_e32 v141, 1.0, v141
	v_add_f32_e32 v142, 1.0, v142
	v_add_f32_e32 v143, 1.0, v143
	v_rcp_f32_e32 v136, v136
	v_rcp_f32_e32 v138, v138
	v_rcp_f32_e32 v139, v139
	v_rcp_f32_e32 v140, v140
	v_rcp_f32_e32 v141, v141
	v_rcp_f32_e32 v142, v142
	v_rcp_f32_e32 v143, v143
	v_pk_mul_f32 v[136:137], v[104:105], v[136:137]
	v_pk_mul_f32 v[138:139], v[106:107], v[138:139]
	v_pk_mul_f32 v[140:141], v[100:101], v[140:141]
	v_pk_mul_f32 v[142:143], v[102:103], v[142:143]
	v_add_u32_e32 v3, 0x18000, v0
	v_cvt_pk_bf16_f32 v136, v136, v137
	v_cvt_pk_bf16_f32 v137, v138, v139
	v_cvt_pk_bf16_f32 v138, v140, v141
	v_cvt_pk_bf16_f32 v139, v142, v143
	global_store_dwordx4 v3, v[136:139], s[4:5] sc1
	v_lshlrev_b32_e32 v3, 16, v132
	v_and_b32_e32 v132, 0xffff0000, v132
	v_mul_f32_e32 v3, 0xbfb8aa3b, v3
	v_exp_f32_e32 v3, v3
	v_mul_f32_e32 v132, 0xbfb8aa3b, v132
	v_lshlrev_b32_e32 v137, 16, v134
	v_and_b32_e32 v138, 0xffff0000, v134
	v_exp_f32_e32 v134, v132
	v_lshlrev_b32_e32 v136, 16, v133
	v_add_f32_e32 v3, 1.0, v3
	v_and_b32_e32 v133, 0xffff0000, v133
	v_rcp_f32_e32 v132, v3
	v_add_f32_e32 v3, 1.0, v134
	v_mul_f32_e32 v134, 0xbfb8aa3b, v136
	v_exp_f32_e32 v134, v134
	v_mul_f32_e32 v133, 0xbfb8aa3b, v133
	v_lshlrev_b32_e32 v139, 16, v135
	v_and_b32_e32 v140, 0xffff0000, v135
	v_exp_f32_e32 v135, v133
	v_rcp_f32_e32 v133, v3
	v_add_f32_e32 v3, 1.0, v134
	v_rcp_f32_e32 v134, v3
	v_add_f32_e32 v3, 1.0, v135
	v_mul_f32_e32 v135, 0xbfb8aa3b, v137
	v_exp_f32_e32 v136, v135
	v_mul_f32_e32 v135, 0xbfb8aa3b, v138
	v_exp_f32_e32 v137, v135
	v_rcp_f32_e32 v135, v3
	v_add_f32_e32 v3, 1.0, v136
	v_rcp_f32_e32 v136, v3
	v_add_f32_e32 v3, 1.0, v137
	v_mul_f32_e32 v137, 0xbfb8aa3b, v139
	v_exp_f32_e32 v138, v137
	v_mul_f32_e32 v137, 0xbfb8aa3b, v140
	v_exp_f32_e32 v139, v137
	v_rcp_f32_e32 v137, v3
	v_add_f32_e32 v3, 1.0, v138
	v_rcp_f32_e32 v138, v3
	v_add_f32_e32 v3, 1.0, v139
	v_rcp_f32_e32 v139, v3
	v_pk_mul_f32 v[132:133], v[72:73], v[132:133]
	v_pk_mul_f32 v[134:135], v[74:75], v[134:135]
	v_pk_mul_f32 v[136:137], v[68:69], v[136:137]
	v_pk_mul_f32 v[138:139], v[70:71], v[138:139]
	v_cvt_pk_bf16_f32 v132, v132, v133
	v_cvt_pk_bf16_f32 v133, v134, v135
	v_cvt_pk_bf16_f32 v134, v136, v137
	v_cvt_pk_bf16_f32 v135, v138, v139
	v_add_u32_e32 v3, 0x18100, v0
	global_store_dwordx4 v3, v[132:135], s[4:5] sc1
	v_add_u32_e32 v3, 0x80000, v2
	global_load_dwordx4 v[170:173], v3, s[94:95] nt
	v_add_u32_e32 v3, 0x80100, v2
	global_load_dwordx4 v[174:177], v3, s[94:95] nt
	v_add_u32_e32 v3, 0x90000, v2
	v_add_u32_e32 v132, 0x90100, v2
	global_load_dwordx4 v[178:181], v3, s[94:95] nt
	global_load_dwordx4 v[148:151], v132, s[94:95] nt
	v_add_u32_e32 v3, 0xa0000, v2
	v_add_u32_e32 v132, 0xa0100, v2
	global_load_dwordx4 v[144:147], v3, s[94:95] nt
	global_load_dwordx4 v[140:143], v132, s[94:95] nt
	v_add_u32_e32 v3, 0xb0000, v2
	v_add_u32_e32 v2, 0xb0100, v2
	global_load_dwordx4 v[136:139], v3, s[94:95] nt
	global_load_dwordx4 v[132:135], v2, s[94:95] nt
	v_add_u32_e32 v169, 0x40000, v0
	s_waitcnt vmcnt(0)
; __device__ __forceinline__ float sigmoidf_(float x) { return __builtin_amdgcn_rcpf(1.0f + __expf(-x)); }
;     __device__ __forceinline__ void operator()(f32x4 (&acc)[2][2][4][2], const pg8::Unit& u, int wr, int wc, int fr, int fq) const {
;     ...
;         for (int ai = 0; ai < 2; ++ai) {
;             u32x4 ga[4][2];
; #pragma unroll
;             for (int m = 0; m < 4; ++m)
; #pragma unroll
;                 for (int bj = 0; bj < 2; ++bj) ga[m][bj] = __builtin_nontemporal_load((const u32x4*)((const char*)Gt + (goff + (unsigned)(ai * 128 + m * 16) * 4096u + 256u * bj)));
; #pragma unroll
;             for (int m = 0; m < 4; ++m) {
;                 const unsigned rm = moff + (unsigned)(ai * 128 + m * 16) * 2048u;
; #pragma unroll
;                 for (int bj = 0; bj < 2; ++bj) {
;                     float fa[8], o[8]; unpack8(ga[m][bj], fa);
; #pragma unroll
;                     for (int e = 0; e < 8; ++e) o[e] = sigmoidf_(fa[e]) * acc[ai][bj][m][e >> 2][e & 3];
;                     *(u32x4*)((char*)MG + (rm + 256u * bj)) = pack8(o);
;                 }
	v_lshlrev_b32_e32 v182, 16, v172
	v_and_b32_e32 v172, 0xffff0000, v172
	v_mul_f32_e32 v182, 0xbfb8aa3b, v182
	v_mul_f32_e32 v172, 0xbfb8aa3b, v172
	v_exp_f32_e32 v182, v182
	v_exp_f32_e32 v184, v172
	v_lshlrev_b32_e32 v2, 16, v170
	v_and_b32_e32 v3, 0xffff0000, v170
	v_lshlrev_b32_e32 v170, 16, v171
	v_and_b32_e32 v171, 0xffff0000, v171
	v_lshlrev_b32_e32 v183, 16, v173
	v_and_b32_e32 v173, 0xffff0000, v173
	v_mul_f32_e32 v2, 0xbfb8aa3b, v2
	v_mul_f32_e32 v3, 0xbfb8aa3b, v3
	v_mul_f32_e32 v170, 0xbfb8aa3b, v170
	v_mul_f32_e32 v171, 0xbfb8aa3b, v171
	v_mul_f32_e32 v183, 0xbfb8aa3b, v183
	v_mul_f32_e32 v173, 0xbfb8aa3b, v173
	v_exp_f32_e32 v2, v2
	v_exp_f32_e32 v3, v3
	v_exp_f32_e32 v170, v170
	v_exp_f32_e32 v171, v171
	v_add_f32_e32 v172, 1.0, v182
	v_add_f32_e32 v182, 1.0, v184
	v_exp_f32_e32 v183, v183
	v_exp_f32_e32 v184, v173
	v_add_f32_e32 v2, 1.0, v2
	v_add_f32_e32 v3, 1.0, v3
	v_add_f32_e32 v170, 1.0, v170
	v_add_f32_e32 v171, 1.0, v171
	v_rcp_f32_e32 v173, v182
	v_add_f32_e32 v182, 1.0, v183
	v_add_f32_e32 v183, 1.0, v184
	v_rcp_f32_e32 v2, v2
	v_rcp_f32_e32 v3, v3
	v_rcp_f32_e32 v170, v170
	v_rcp_f32_e32 v171, v171
	v_rcp_f32_e32 v172, v172
	v_rcp_f32_e32 v182, v182
	v_rcp_f32_e32 v183, v183
	v_pk_mul_f32 v[2:3], v[64:65], v[2:3]
	v_pk_mul_f32 v[184:185], v[66:67], v[170:171]
	v_pk_mul_f32 v[172:173], v[60:61], v[172:173]
	v_pk_mul_f32 v[182:183], v[62:63], v[182:183]
	v_cvt_pk_bf16_f32 v170, v2, v3
	v_cvt_pk_bf16_f32 v171, v184, v185
	v_cvt_pk_bf16_f32 v172, v172, v173
	v_cvt_pk_bf16_f32 v173, v182, v183
	global_store_dwordx4 v169, v[170:173], s[4:5] sc1
	v_lshlrev_b32_e32 v169, 16, v175
	v_mul_f32_e32 v169, 0xbfb8aa3b, v169
	v_and_b32_e32 v170, 0xffff0000, v175
	v_exp_f32_e32 v169, v169
	v_mul_f32_e32 v170, 0xbfb8aa3b, v170
	v_exp_f32_e32 v175, v170
	v_lshlrev_b32_e32 v171, 16, v176
	v_and_b32_e32 v172, 0xffff0000, v176
	v_add_f32_e32 v169, 1.0, v169
	v_mul_f32_e32 v171, 0xbfb8aa3b, v171
	v_rcp_f32_e32 v170, v169
	v_add_f32_e32 v169, 1.0, v175
	v_exp_f32_e32 v175, v171
	v_mul_f32_e32 v171, 0xbfb8aa3b, v172
	v_exp_f32_e32 v176, v171
	v_lshlrev_b32_e32 v173, 16, v177
	v_lshlrev_b32_e32 v2, 16, v174
	v_and_b32_e32 v3, 0xffff0000, v174
	v_and_b32_e32 v174, 0xffff0000, v177
	v_mul_f32_e32 v173, 0xbfb8aa3b, v173
	v_mul_f32_e32 v2, 0xbfb8aa3b, v2
	v_mul_f32_e32 v3, 0xbfb8aa3b, v3
	v_rcp_f32_e32 v171, v169
	v_add_f32_e32 v169, 1.0, v175
	v_exp_f32_e32 v175, v173
	v_mul_f32_e32 v173, 0xbfb8aa3b, v174
	v_exp_f32_e32 v2, v2
	v_exp_f32_e32 v3, v3
	v_rcp_f32_e32 v172, v169
	v_add_f32_e32 v169, 1.0, v176
	v_exp_f32_e32 v176, v173
	v_rcp_f32_e32 v173, v169
	v_add_f32_e32 v169, 1.0, v175
	v_add_f32_e32 v2, 1.0, v2
	v_add_f32_e32 v3, 1.0, v3
	v_rcp_f32_e32 v174, v169
	v_add_f32_e32 v169, 1.0, v176
	v_rcp_f32_e32 v2, v2
	v_rcp_f32_e32 v3, v3
	v_rcp_f32_e32 v175, v169
	v_pk_mul_f32 v[176:177], v[34:35], v[170:171]
	v_pk_mul_f32 v[172:173], v[28:29], v[172:173]
	v_pk_mul_f32 v[2:3], v[32:33], v[2:3]
	v_pk_mul_f32 v[174:175], v[30:31], v[174:175]
	v_cvt_pk_bf16_f32 v170, v2, v3
	v_cvt_pk_bf16_f32 v171, v176, v177
	v_cvt_pk_bf16_f32 v172, v172, v173
	v_cvt_pk_bf16_f32 v173, v174, v175
	v_add_u32_e32 v2, 0x40100, v0
	global_store_dwordx4 v2, v[170:173], s[4:5] sc1
	v_lshlrev_b32_e32 v2, 16, v178
	v_and_b32_e32 v3, 0xffff0000, v178
	v_lshlrev_b32_e32 v170, 16, v179
	v_and_b32_e32 v171, 0xffff0000, v179
	v_lshlrev_b32_e32 v172, 16, v180
	v_and_b32_e32 v173, 0xffff0000, v180
	v_lshlrev_b32_e32 v174, 16, v181
	v_and_b32_e32 v175, 0xffff0000, v181
	v_mul_f32_e32 v2, 0xbfb8aa3b, v2
	v_mul_f32_e32 v3, 0xbfb8aa3b, v3
	v_mul_f32_e32 v170, 0xbfb8aa3b, v170
	v_mul_f32_e32 v171, 0xbfb8aa3b, v171
	v_mul_f32_e32 v172, 0xbfb8aa3b, v172
	v_mul_f32_e32 v173, 0xbfb8aa3b, v173
	v_mul_f32_e32 v174, 0xbfb8aa3b, v174
	v_mul_f32_e32 v175, 0xbfb8aa3b, v175
	v_exp_f32_e32 v2, v2
	v_exp_f32_e32 v3, v3
	v_exp_f32_e32 v170, v170
	v_exp_f32_e32 v171, v171
	v_exp_f32_e32 v172, v172
	v_exp_f32_e32 v173, v173
	v_exp_f32_e32 v174, v174
	v_exp_f32_e32 v175, v175
	v_add_f32_e32 v2, 1.0, v2
	v_add_f32_e32 v3, 1.0, v3
	v_add_f32_e32 v170, 1.0, v170
	v_add_f32_e32 v171, 1.0, v171
	v_add_f32_e32 v172, 1.0, v172
	v_add_f32_e32 v173, 1.0, v173
	v_add_f32_e32 v174, 1.0, v174
	v_add_f32_e32 v175, 1.0, v175
	v_rcp_f32_e32 v2, v2
	v_rcp_f32_e32 v3, v3
	v_rcp_f32_e32 v170, v170
	v_rcp_f32_e32 v171, v171
	v_rcp_f32_e32 v172, v172
	v_rcp_f32_e32 v173, v173
	v_rcp_f32_e32 v174, v174
	v_rcp_f32_e32 v175, v175
	v_pk_mul_f32 v[2:3], v[56:57], v[2:3]
	v_pk_mul_f32 v[176:177], v[58:59], v[170:171]
	v_pk_mul_f32 v[172:173], v[52:53], v[172:173]
	v_pk_mul_f32 v[174:175], v[54:55], v[174:175]
	v_add_u32_e32 v169, 0x48000, v0
	v_cvt_pk_bf16_f32 v170, v2, v3
	v_cvt_pk_bf16_f32 v171, v176, v177
	v_cvt_pk_bf16_f32 v172, v172, v173
	v_cvt_pk_bf16_f32 v173, v174, v175
	global_store_dwordx4 v169, v[170:173], s[4:5] sc1
	v_lshlrev_b32_e32 v169, 16, v150
	v_and_b32_e32 v150, 0xffff0000, v150
	v_mul_f32_e32 v169, 0xbfb8aa3b, v169
	v_mul_f32_e32 v150, 0xbfb8aa3b, v150
	v_exp_f32_e32 v169, v169
	v_exp_f32_e32 v171, v150
	v_lshlrev_b32_e32 v170, 16, v151
	v_lshlrev_b32_e32 v2, 16, v148
	v_and_b32_e32 v3, 0xffff0000, v148
	v_lshlrev_b32_e32 v148, 16, v149
	v_and_b32_e32 v149, 0xffff0000, v149
	v_and_b32_e32 v151, 0xffff0000, v151
	v_mul_f32_e32 v170, 0xbfb8aa3b, v170
	v_mul_f32_e32 v2, 0xbfb8aa3b, v2
	v_mul_f32_e32 v3, 0xbfb8aa3b, v3
	v_mul_f32_e32 v148, 0xbfb8aa3b, v148
	v_mul_f32_e32 v149, 0xbfb8aa3b, v149
	v_exp_f32_e32 v170, v170
	v_mul_f32_e32 v151, 0xbfb8aa3b, v151
	v_exp_f32_e32 v2, v2
	v_exp_f32_e32 v3, v3
	v_exp_f32_e32 v148, v148
	v_exp_f32_e32 v149, v149
	v_add_f32_e32 v150, 1.0, v169
	v_add_f32_e32 v169, 1.0, v171
; __device__ __forceinline__ float sigmoidf_(float x) { return __builtin_amdgcn_rcpf(1.0f + __expf(-x)); }
;     __device__ __forceinline__ void operator()(f32x4 (&acc)[2][2][4][2], const pg8::Unit& u, int wr, int wc, int fr, int fq) const {
;     ...
;             for (int m = 0; m < 4; ++m) {
;                 const unsigned rm = moff + (unsigned)(ai * 128 + m * 16) * 2048u;
; #pragma unroll
;                 for (int bj = 0; bj < 2; ++bj) {
;                     float fa[8], o[8]; unpack8(ga[m][bj], fa);
; #pragma unroll
;                     for (int e = 0; e < 8; ++e) o[e] = sigmoidf_(fa[e]) * acc[ai][bj][m][e >> 2][e & 3];
;                     *(u32x4*)((char*)MG + (rm + 256u * bj)) = pack8(o);
;                 }
	v_exp_f32_e32 v171, v151
	v_rcp_f32_e32 v151, v169
	v_add_f32_e32 v169, 1.0, v170
	v_add_f32_e32 v2, 1.0, v2
	v_add_f32_e32 v3, 1.0, v3
	v_add_f32_e32 v148, 1.0, v148
	v_add_f32_e32 v149, 1.0, v149
	v_rcp_f32_e32 v170, v169
	v_add_f32_e32 v169, 1.0, v171
	v_rcp_f32_e32 v2, v2
	v_rcp_f32_e32 v3, v3
	v_rcp_f32_e32 v148, v148
	v_rcp_f32_e32 v149, v149
	v_rcp_f32_e32 v150, v150
	v_rcp_f32_e32 v171, v169
	v_pk_mul_f32 v[2:3], v[24:25], v[2:3]
	v_pk_mul_f32 v[172:173], v[26:27], v[148:149]
	v_pk_mul_f32 v[150:151], v[20:21], v[150:151]
	v_pk_mul_f32 v[170:171], v[22:23], v[170:171]
	v_cvt_pk_bf16_f32 v148, v2, v3
	v_cvt_pk_bf16_f32 v149, v172, v173
	v_cvt_pk_bf16_f32 v150, v150, v151
	v_cvt_pk_bf16_f32 v151, v170, v171
	v_add_u32_e32 v2, 0x48100, v0
	global_store_dwordx4 v2, v[148:151], s[4:5] sc1
	v_lshlrev_b32_e32 v2, 16, v144
	v_and_b32_e32 v3, 0xffff0000, v144
	v_lshlrev_b32_e32 v148, 16, v146
	v_and_b32_e32 v146, 0xffff0000, v146
	v_mul_f32_e32 v148, 0xbfb8aa3b, v148
	v_mul_f32_e32 v146, 0xbfb8aa3b, v146
	v_exp_f32_e32 v148, v148
	v_exp_f32_e32 v150, v146
	v_lshlrev_b32_e32 v144, 16, v145
	v_and_b32_e32 v145, 0xffff0000, v145
	v_lshlrev_b32_e32 v149, 16, v147
	v_and_b32_e32 v147, 0xffff0000, v147
	v_mul_f32_e32 v2, 0xbfb8aa3b, v2
	v_mul_f32_e32 v3, 0xbfb8aa3b, v3
	v_mul_f32_e32 v144, 0xbfb8aa3b, v144
	v_mul_f32_e32 v145, 0xbfb8aa3b, v145
	v_mul_f32_e32 v149, 0xbfb8aa3b, v149
	v_mul_f32_e32 v147, 0xbfb8aa3b, v147
	v_exp_f32_e32 v2, v2
	v_exp_f32_e32 v3, v3
	v_exp_f32_e32 v144, v144
	v_exp_f32_e32 v145, v145
	v_add_f32_e32 v146, 1.0, v148
	v_add_f32_e32 v148, 1.0, v150
	v_exp_f32_e32 v149, v149
	v_exp_f32_e32 v150, v147
	v_add_f32_e32 v2, 1.0, v2
	v_add_f32_e32 v3, 1.0, v3
	v_add_f32_e32 v144, 1.0, v144
	v_add_f32_e32 v145, 1.0, v145
	v_rcp_f32_e32 v147, v148
	v_add_f32_e32 v148, 1.0, v149
	v_add_f32_e32 v149, 1.0, v150
	v_rcp_f32_e32 v2, v2
	v_rcp_f32_e32 v3, v3
	v_rcp_f32_e32 v144, v144
	v_rcp_f32_e32 v145, v145
	v_rcp_f32_e32 v146, v146
	v_rcp_f32_e32 v148, v148
	v_rcp_f32_e32 v149, v149
	v_pk_mul_f32 v[2:3], v[48:49], v[2:3]
	v_pk_mul_f32 v[150:151], v[50:51], v[144:145]
	v_pk_mul_f32 v[146:147], v[44:45], v[146:147]
	v_pk_mul_f32 v[148:149], v[46:47], v[148:149]
	v_add_u32_e32 v169, 0x50000, v0
	v_cvt_pk_bf16_f32 v144, v2, v3
	v_cvt_pk_bf16_f32 v145, v150, v151
	v_cvt_pk_bf16_f32 v146, v146, v147
	v_cvt_pk_bf16_f32 v147, v148, v149
	global_store_dwordx4 v169, v[144:147], s[4:5] sc1
	v_lshlrev_b32_e32 v2, 16, v140
	v_and_b32_e32 v3, 0xffff0000, v140
	v_lshlrev_b32_e32 v144, 16, v142
	v_and_b32_e32 v142, 0xffff0000, v142
	v_mul_f32_e32 v144, 0xbfb8aa3b, v144
	v_mul_f32_e32 v142, 0xbfb8aa3b, v142
	v_exp_f32_e32 v144, v144
	v_exp_f32_e32 v146, v142
	v_lshlrev_b32_e32 v140, 16, v141
	v_and_b32_e32 v141, 0xffff0000, v141
	v_lshlrev_b32_e32 v145, 16, v143
	v_and_b32_e32 v143, 0xffff0000, v143
	v_mul_f32_e32 v2, 0xbfb8aa3b, v2
	v_mul_f32_e32 v3, 0xbfb8aa3b, v3
	v_mul_f32_e32 v140, 0xbfb8aa3b, v140
	v_mul_f32_e32 v141, 0xbfb8aa3b, v141
	v_mul_f32_e32 v145, 0xbfb8aa3b, v145
	v_mul_f32_e32 v143, 0xbfb8aa3b, v143
	v_exp_f32_e32 v2, v2
	v_exp_f32_e32 v3, v3
	v_exp_f32_e32 v140, v140
	v_exp_f32_e32 v141, v141
	v_add_f32_e32 v142, 1.0, v144
	v_add_f32_e32 v144, 1.0, v146
	v_exp_f32_e32 v145, v145
	v_exp_f32_e32 v146, v143
	v_add_f32_e32 v2, 1.0, v2
	v_add_f32_e32 v3, 1.0, v3
	v_add_f32_e32 v140, 1.0, v140
	v_add_f32_e32 v141, 1.0, v141
	v_rcp_f32_e32 v143, v144
	v_add_f32_e32 v144, 1.0, v145
	v_add_f32_e32 v145, 1.0, v146
	v_rcp_f32_e32 v2, v2
	v_rcp_f32_e32 v3, v3
	v_rcp_f32_e32 v140, v140
	v_rcp_f32_e32 v141, v141
	v_rcp_f32_e32 v142, v142
	v_rcp_f32_e32 v144, v144
	v_rcp_f32_e32 v145, v145
; __device__ __forceinline__ float sigmoidf_(float x) { return __builtin_amdgcn_rcpf(1.0f + __expf(-x)); }
;     __device__ __forceinline__ void operator()(f32x4 (&acc)[2][2][4][2], const pg8::Unit& u, int wr, int wc, int fr, int fq) const {
;     ...
;             for (int m = 0; m < 4; ++m) {
;                 const unsigned rm = moff + (unsigned)(ai * 128 + m * 16) * 2048u;
; #pragma unroll
;                 for (int bj = 0; bj < 2; ++bj) {
;                     float fa[8], o[8]; unpack8(ga[m][bj], fa);
; #pragma unroll
;                     for (int e = 0; e < 8; ++e) o[e] = sigmoidf_(fa[e]) * acc[ai][bj][m][e >> 2][e & 3];
;                     *(u32x4*)((char*)MG + (rm + 256u * bj)) = pack8(o);
;                 }
	v_pk_mul_f32 v[2:3], v[16:17], v[2:3]
	v_pk_mul_f32 v[146:147], v[18:19], v[140:141]
	v_pk_mul_f32 v[142:143], v[12:13], v[142:143]
	v_pk_mul_f32 v[144:145], v[14:15], v[144:145]
	v_cvt_pk_bf16_f32 v140, v2, v3
	v_cvt_pk_bf16_f32 v141, v146, v147
	v_cvt_pk_bf16_f32 v142, v142, v143
	v_cvt_pk_bf16_f32 v143, v144, v145
	v_add_u32_e32 v2, 0x50100, v0
	global_store_dwordx4 v2, v[140:143], s[4:5] sc1
	v_lshlrev_b32_e32 v2, 16, v136
	v_and_b32_e32 v3, 0xffff0000, v136
	v_lshlrev_b32_e32 v140, 16, v138
	v_and_b32_e32 v138, 0xffff0000, v138
	v_mul_f32_e32 v140, 0xbfb8aa3b, v140
	v_mul_f32_e32 v138, 0xbfb8aa3b, v138
	v_exp_f32_e32 v140, v140
	v_exp_f32_e32 v142, v138
	v_lshlrev_b32_e32 v136, 16, v137
	v_and_b32_e32 v137, 0xffff0000, v137
	v_lshlrev_b32_e32 v141, 16, v139
	v_and_b32_e32 v139, 0xffff0000, v139
	v_mul_f32_e32 v2, 0xbfb8aa3b, v2
	v_mul_f32_e32 v3, 0xbfb8aa3b, v3
	v_mul_f32_e32 v136, 0xbfb8aa3b, v136
	v_mul_f32_e32 v137, 0xbfb8aa3b, v137
	v_mul_f32_e32 v141, 0xbfb8aa3b, v141
	v_mul_f32_e32 v139, 0xbfb8aa3b, v139
	v_exp_f32_e32 v2, v2
	v_exp_f32_e32 v3, v3
	v_exp_f32_e32 v136, v136
	v_exp_f32_e32 v137, v137
	v_add_f32_e32 v138, 1.0, v140
	v_add_f32_e32 v140, 1.0, v142
	v_exp_f32_e32 v141, v141
	v_exp_f32_e32 v142, v139
	v_add_f32_e32 v2, 1.0, v2
	v_add_f32_e32 v3, 1.0, v3
	v_add_f32_e32 v136, 1.0, v136
	v_add_f32_e32 v137, 1.0, v137
	v_rcp_f32_e32 v139, v140
	v_add_f32_e32 v140, 1.0, v141
	v_add_f32_e32 v141, 1.0, v142
	v_rcp_f32_e32 v2, v2
	v_rcp_f32_e32 v3, v3
	v_rcp_f32_e32 v136, v136
	v_rcp_f32_e32 v137, v137
	v_rcp_f32_e32 v138, v138
	v_rcp_f32_e32 v140, v140
	v_rcp_f32_e32 v141, v141
	v_pk_mul_f32 v[2:3], v[40:41], v[2:3]
	v_pk_mul_f32 v[142:143], v[42:43], v[136:137]
	v_pk_mul_f32 v[138:139], v[36:37], v[138:139]
	v_pk_mul_f32 v[140:141], v[38:39], v[140:141]
	v_add_u32_e32 v144, 0x58000, v0
	v_cvt_pk_bf16_f32 v136, v2, v3
	v_cvt_pk_bf16_f32 v137, v142, v143
	v_cvt_pk_bf16_f32 v138, v138, v139
	v_cvt_pk_bf16_f32 v139, v140, v141
	global_store_dwordx4 v144, v[136:139], s[4:5] sc1
	v_lshlrev_b32_e32 v2, 16, v132
	v_and_b32_e32 v3, 0xffff0000, v132
	v_lshlrev_b32_e32 v136, 16, v134
	v_and_b32_e32 v134, 0xffff0000, v134
	v_mul_f32_e32 v136, 0xbfb8aa3b, v136
	v_mul_f32_e32 v134, 0xbfb8aa3b, v134
	v_exp_f32_e32 v136, v136
	v_exp_f32_e32 v138, v134
	v_lshlrev_b32_e32 v132, 16, v133
	v_and_b32_e32 v133, 0xffff0000, v133
	v_lshlrev_b32_e32 v137, 16, v135
	v_and_b32_e32 v135, 0xffff0000, v135
	v_mul_f32_e32 v2, 0xbfb8aa3b, v2
	v_mul_f32_e32 v3, 0xbfb8aa3b, v3
	v_mul_f32_e32 v132, 0xbfb8aa3b, v132
	v_mul_f32_e32 v133, 0xbfb8aa3b, v133
	v_mul_f32_e32 v137, 0xbfb8aa3b, v137
	v_mul_f32_e32 v135, 0xbfb8aa3b, v135
	v_exp_f32_e32 v2, v2
	v_exp_f32_e32 v3, v3
	v_exp_f32_e32 v132, v132
	v_exp_f32_e32 v133, v133
	v_add_f32_e32 v134, 1.0, v136
	v_add_f32_e32 v136, 1.0, v138
	v_exp_f32_e32 v137, v137
	v_exp_f32_e32 v138, v135
	v_add_f32_e32 v2, 1.0, v2
	v_add_f32_e32 v3, 1.0, v3
	v_add_f32_e32 v132, 1.0, v132
	v_add_f32_e32 v133, 1.0, v133
	v_rcp_f32_e32 v135, v136
	v_add_f32_e32 v136, 1.0, v137
	v_add_f32_e32 v137, 1.0, v138
	v_rcp_f32_e32 v2, v2
	v_rcp_f32_e32 v3, v3
	v_rcp_f32_e32 v132, v132
	v_rcp_f32_e32 v133, v133
	v_rcp_f32_e32 v134, v134
	v_rcp_f32_e32 v136, v136
	v_rcp_f32_e32 v137, v137
	v_pk_mul_f32 v[2:3], v[8:9], v[2:3]
	v_pk_mul_f32 v[138:139], v[10:11], v[132:133]
	v_pk_mul_f32 v[134:135], v[4:5], v[134:135]
	v_pk_mul_f32 v[136:137], v[6:7], v[136:137]
	v_cvt_pk_bf16_f32 v132, v2, v3
	v_cvt_pk_bf16_f32 v133, v138, v139
	v_cvt_pk_bf16_f32 v134, v134, v135
	v_cvt_pk_bf16_f32 v135, v136, v137
	v_add_u32_e32 v0, 0x58100, v0
	global_store_dwordx4 v0, v[132:135], s[4:5] sc1
